# gdn_prep: team 1 (waves 4-7) starts ~12us after team 0 so the two teams' load-heavy and VALU-heavy stages interleave on each SIMD
# baseline (speedup 1.0000x reference)
.LBB0_441:
	s_cmp_lt_i32 s78, 4
	s_cselect_b64 s[8:9], -1, 0
	s_and_b64 s[4:5], s[8:9], s[4:5]
	s_andn2_b64 vcc, exec, s[4:5]
	s_cbranch_vccnz .LBB0_603
	v_writelane_b32 v255, s8, 5
	v_and_b32_e32 v137, 0x3ff, v0
	v_cmp_gt_u32_e32 vcc, 2, v137
	v_writelane_b32 v255, s9, 6
	v_lshl_add_u32 v139, v137, 2, 0
	s_and_saveexec_b64 s[4:5], vcc
	v_mov_b32_e32 v2, 0
	ds_write_b32 v139, v2 offset:36352
	s_or_b64 exec, exec, s[4:5]
	v_lshrrev_b32_e32 v2, 8, v137
	v_mul_lo_u32 v3, s33, v2
	v_add_u32_e32 v141, s2, v3
	s_movk_i32 s3, 0x800
	v_cmp_gt_i32_e32 vcc, s3, v141
	v_and_b32_e32 v119, 63, v137
	s_waitcnt vmcnt(0) lgkmcnt(0)
	s_barrier
	s_and_saveexec_b64 s[10:11], vcc
	s_cbranch_execz .LBB0_524
	v_readfirstlane_b32 s4, v2
	s_cmp_eq_u32 s4, 0
	s_cbranch_scc1 .Lp3_nostagger
	s_sleep 127
	s_sleep 127
	s_sleep 127
.Lp3_nostagger:
	s_mov_b32 s4, 0x14000
	v_mbcnt_lo_u32_b32 v171, -1, 0
	v_mad_u32_u24 v143, v2, s4, 0
	v_mul_i32_i24_e32 v2, 0xfffec004, v2
	v_mbcnt_hi_u32_b32 v172, -1, v171
	s_mov_b32 s3, 0
	v_and_b32_e32 v162, 0xff, v137
	v_add_u32_e32 v163, 0x4400, v143
	v_add_u32_e32 v164, 0x8900, v143
	v_add_u32_e32 v167, 0x8b00, v143
	v_add_u32_e32 v168, 0xb000, v143
	v_cmp_eq_u32_e64 s[4:5], 0, v119
	s_lshl_b32 s47, s33, 1
	s_mov_b64 s[12:13], 0
	v_add_u32_e32 v169, v143, v2
	v_mov_b32_e32 v170, 1
	s_mov_b32 s64, 0x12100
	s_mov_b64 s[14:15], 0x15b38000
	v_and_b32_e32 v173, 64, v172
	v_mov_b32_e32 v99, 0
	s_mov_b64 s[16:17], 0x62b0000
	s_mov_b32 s65, 0x41a00000
	s_mov_b32 s66, 0x3f2aaaab
	v_mov_b32_e32 v174, 0x3ecc95a3
	s_mov_b32 s67, 0x3f317218
	s_mov_b32 s68, 0x7f800000
	s_mov_b32 s69, 0x33800000
	s_mov_b64 s[18:19], 0xa5b8000
	s_mov_b64 s[20:21], 0xa5b9000
	s_mov_b64 s[22:23], 0x3000
	s_mov_b64 s[24:25], 0x6000
	s_mov_b64 s[26:27], 0x9000
	s_mov_b64 s[28:29], 0x1000
	s_mov_b64 s[30:31], 0x4000
	s_mov_b64 s[34:35], 0x7000
	s_mov_b64 s[36:37], 0xa000
	s_mov_b64 s[38:39], 0x2000
	s_mov_b64 s[40:41], 0x5000
	s_mov_b64 s[42:43], 0x8000
	s_mov_b64 s[44:45], 0xb000
	s_movk_i32 s70, 0x2c00
	s_movk_i32 s71, 0x110
	s_mov_b32 s46, 0x358637bd
	s_mov_b32 s72, 0x800000
	s_movk_i32 s73, 0x3000
	s_mov_b64 s[48:49], 0x8400000
	s_mov_b32 s74, 0x8401000
	s_movk_i32 s75, 0x80
	s_movk_i32 s80, 0x210
	s_mov_b64 s[50:51], 0xe000
	s_movk_i32 s81, 0x7ff
	v_mov_b32_e32 v100, 0x3f317218
	v_mov_b32_e32 v175, 0x7f800000
	v_mov_b32_e32 v176, 0x7fc00000
	v_mov_b32_e32 v177, 0xff800000
	v_not_b32_e32 v178, 60
	s_branch .LBB0_447
